# phase A column-mapped transpose tile: sixteen guarded loads issued together, one wait, then the LDS writes (prologue de-serialisation)
# baseline (speedup 1.0000x reference)
; template <class Map>
; __device__ __forceinline__ void tconv_tile(const float* __restrict__ src, int ldsrc, bf16_t* __restrict__ dst, int ldd, int n0, int k0, Map map, float* t) {
;     const int tid = TIDX;
;     const int n = tid & 63, kb = tid >> 6;
;     const int sc = map(n0 + n);
; #pragma unroll
;     for (int i = 0; i < 16; i++) { const int k = i * 4 + kb; t[k * 65 + n] = sc >= 0 ? src[(size_t)(k0 + k) * ldsrc + sc] : 0.f; }
;     __syncthreads();
;     const int nn = tid >> 2, kk = (tid & 3) * 16;
;     unsigned w[8];
; #pragma unroll
;     for (int j = 0; j < 8; j++) w[j] = pack2(t[(kk + 2 * j) * 65 + nn], t[(kk + 2 * j + 1) * 65 + nn]);
;     u32x4* d = (u32x4*)(dst + (size_t)(n0 + nn) * ldd + k0 + kk);
;     d[0] = (u32x4){w[0], w[1], w[2], w[3]};
;     d[1] = (u32x4){w[4], w[5], w[6], w[7]};
;     __syncthreads();
; }
.LBB0_38:
	s_lshl_b32 s42, s71, 6
	s_and_b32 s44, s42, 0x3c0
	v_bfe_u32 v4, v2, 6, 2
	v_cmp_lt_i32_e32 vcc, -1, v3
	v_mov_b32_e32 v100, 0
	v_mov_b32_e32 v101, 0
	v_mov_b32_e32 v106, 0
	v_mov_b32_e32 v107, 0
	v_mov_b32_e32 v108, 0
	v_mov_b32_e32 v109, 0
	v_mov_b32_e32 v110, 0
	v_mov_b32_e32 v111, 0
	v_mov_b32_e32 v112, 0
	v_mov_b32_e32 v113, 0
	v_mov_b32_e32 v114, 0
	v_mov_b32_e32 v115, 0
	v_mov_b32_e32 v116, 0
	v_mov_b32_e32 v117, 0
	v_mov_b32_e32 v118, 0
	v_mov_b32_e32 v119, 0
	s_waitcnt lgkmcnt(0)
	s_and_saveexec_b64 s[42:43], vcc
	s_cbranch_execz .La_tc_skip
	v_or_b32_e32 v6, s44, v4
	v_mad_u32_u24 v102, v6, s54, v3
	v_lshl_add_u64 v[8:9], v[102:103], 2, s[40:41]
	global_load_dword v100, v[8:9], off
	v_or3_b32 v6, v4, s44, 4
	v_mad_u32_u24 v102, v6, s54, v3
	v_lshl_add_u64 v[8:9], v[102:103], 2, s[40:41]
	global_load_dword v101, v[8:9], off
	v_or3_b32 v6, v4, s44, 8
	v_mad_u32_u24 v102, v6, s54, v3
	v_lshl_add_u64 v[8:9], v[102:103], 2, s[40:41]
	global_load_dword v106, v[8:9], off
	v_or3_b32 v6, v4, s44, 12
	v_mad_u32_u24 v102, v6, s54, v3
	v_lshl_add_u64 v[8:9], v[102:103], 2, s[40:41]
	global_load_dword v107, v[8:9], off
	v_or3_b32 v6, v4, s44, 16
	v_mad_u32_u24 v102, v6, s54, v3
	v_lshl_add_u64 v[8:9], v[102:103], 2, s[40:41]
	global_load_dword v108, v[8:9], off
	v_or3_b32 v6, v4, s44, 20
	v_mad_u32_u24 v102, v6, s54, v3
	v_lshl_add_u64 v[8:9], v[102:103], 2, s[40:41]
	global_load_dword v109, v[8:9], off
	v_or3_b32 v6, v4, s44, 24
	v_mad_u32_u24 v102, v6, s54, v3
	v_lshl_add_u64 v[8:9], v[102:103], 2, s[40:41]
	global_load_dword v110, v[8:9], off
	v_or3_b32 v6, v4, s44, 28
	v_mad_u32_u24 v102, v6, s54, v3
	v_lshl_add_u64 v[8:9], v[102:103], 2, s[40:41]
	global_load_dword v111, v[8:9], off
	v_or3_b32 v6, v4, s44, 32
	v_mad_u32_u24 v102, v6, s54, v3
	v_lshl_add_u64 v[8:9], v[102:103], 2, s[40:41]
	global_load_dword v112, v[8:9], off
	v_or3_b32 v6, v4, s44, 36
	v_mad_u32_u24 v102, v6, s54, v3
	v_lshl_add_u64 v[8:9], v[102:103], 2, s[40:41]
	global_load_dword v113, v[8:9], off
	v_or3_b32 v6, v4, s44, 40
	v_mad_u32_u24 v102, v6, s54, v3
	v_lshl_add_u64 v[8:9], v[102:103], 2, s[40:41]
	global_load_dword v114, v[8:9], off
	v_or3_b32 v6, v4, s44, 44
	v_mad_u32_u24 v102, v6, s54, v3
	v_lshl_add_u64 v[8:9], v[102:103], 2, s[40:41]
	global_load_dword v115, v[8:9], off
	v_or3_b32 v6, v4, s44, 48
	v_mad_u32_u24 v102, v6, s54, v3
	v_lshl_add_u64 v[8:9], v[102:103], 2, s[40:41]
	global_load_dword v116, v[8:9], off
	v_or3_b32 v6, v4, s44, 52
	v_mad_u32_u24 v102, v6, s54, v3
	v_lshl_add_u64 v[8:9], v[102:103], 2, s[40:41]
	global_load_dword v117, v[8:9], off
	v_or3_b32 v6, v4, s44, 56
	v_mad_u32_u24 v102, v6, s54, v3
	v_lshl_add_u64 v[8:9], v[102:103], 2, s[40:41]
	global_load_dword v118, v[8:9], off
	v_or3_b32 v6, v4, s44, 60
	v_mad_u32_u24 v102, v6, s54, v3
	v_lshl_add_u64 v[8:9], v[102:103], 2, s[40:41]
	global_load_dword v119, v[8:9], off
.La_tc_skip:
	s_or_b64 exec, exec, s[42:43]
	v_mul_u32_u24_e32 v7, 0x104, v4
	v_lshlrev_b32_e32 v5, 2, v5
	v_add3_u32 v9, s33, v7, v5
	s_waitcnt vmcnt(0)
	ds_write_b32 v9, v100
	ds_write_b32 v9, v101 offset:1040
	ds_write_b32 v9, v106 offset:2080
	ds_write_b32 v9, v107 offset:3120
	ds_write_b32 v9, v108 offset:4160
	ds_write_b32 v9, v109 offset:5200
	ds_write_b32 v9, v110 offset:6240
	ds_write_b32 v9, v111 offset:7280
	ds_write_b32 v9, v112 offset:8320
	ds_write_b32 v9, v113 offset:9360
	ds_write_b32 v9, v114 offset:10400
	ds_write_b32 v9, v115 offset:11440
	ds_write_b32 v9, v116 offset:12480
	ds_write_b32 v9, v117 offset:13520
	ds_write_b32 v9, v118 offset:14560
	ds_write_b32 v9, v119 offset:15600
	v_lshlrev_b32_e32 v3, 4, v2
	v_and_b32_e32 v16, 48, v3
	v_mul_u32_u24_e32 v3, 0x41, v16
	v_lshlrev_b32_e32 v3, 2, v3
	v_and_b32_sdwa v6, v2, s1 dst_sel:DWORD dst_unused:UNUSED_PAD src0_sel:BYTE_0 src1_sel:DWORD
	v_add3_u32 v14, s33, v3, v6
	v_add3_u32 v3, s33, v6, v3
	v_add_u32_e32 v6, 0x200, v14
	s_waitcnt lgkmcnt(0)
	s_barrier
	ds_read2_b32 v[4:5], v14 offset1:130
	ds_read_b32 v3, v3 offset:260
	ds_read_b32 v18, v14 offset:3900
	ds_read2_b32 v[6:7], v6 offset0:67 offset1:132
	v_lshrrev_b32_sdwa v17, v137, v2 dst_sel:DWORD dst_unused:UNUSED_PAD src0_sel:DWORD src1_sel:BYTE_0
	s_waitcnt lgkmcnt(2)
	v_cvt_pk_bf16_f32 v2, v4, v3
	v_add_u32_e32 v4, 0x400, v14
	s_waitcnt lgkmcnt(0)
	v_cvt_pk_bf16_f32 v3, v5, v6
	v_add_u32_e32 v6, 0x600, v14
	ds_read2_b32 v[8:9], v6 offset0:71 offset1:136
	v_add_u32_e32 v6, 0x800, v14
	ds_read2_b32 v[10:11], v6 offset0:73 offset1:138
	v_add_u32_e32 v6, 0xa00, v14
	ds_read2_b32 v[4:5], v4 offset0:69 offset1:134
	ds_read2_b32 v[12:13], v6 offset0:75 offset1:140
	v_add_u32_e32 v6, 0xc00, v14
	ds_read2_b32 v[14:15], v6 offset0:77 offset1:142
	s_waitcnt lgkmcnt(3)
	v_cvt_pk_bf16_f32 v6, v9, v10
	v_or_b32_e32 v10, s26, v17
	v_lshlrev_b32_e32 v102, 11, v10
	s_waitcnt lgkmcnt(2)
	v_cvt_pk_bf16_f32 v4, v7, v4
	s_waitcnt lgkmcnt(1)
	v_cvt_pk_bf16_f32 v7, v11, v12
	v_lshl_add_u64 v[10:11], s[4:5], 0, v[102:103]
	s_lshl_b32 s26, s44, 1
	v_lshl_add_u64 v[10:11], v[10:11], 0, s[26:27]
	v_lshlrev_b32_e32 v102, 1, v16
	v_lshl_add_u64 v[10:11], v[10:11], 0, v[102:103]
	v_cvt_pk_bf16_f32 v5, v5, v8
	s_waitcnt lgkmcnt(0)
	v_cvt_pk_bf16_f32 v8, v13, v14
	v_lshl_add_u64 v[12:13], v[10:11], 0, s[34:35]
	v_add_co_u32_e32 v10, vcc, 0x400000, v10
	v_cvt_pk_bf16_f32 v9, v15, v18
	s_nop 0
	v_addc_co_u32_e32 v11, vcc, 0, v11, vcc
	global_store_dwordx4 v[10:11], v[2:5], off
	global_store_dwordx4 v[12:13], v[6:9], off offset:16
	s_barrier
